# P4: hand-written fp8 weight-copy path; copy workgroups join the scan ticket queue when done; later code kept at baseline byte offsets
# speedup vs baseline: 1.0063x; 1.0012x over previous
.Lcp_entry:
	v_readfirstlane_b32 s0, v184
	v_and_b32_e32 v202, 63, v184
	s_lshr_b32 s0, s0, 6
	s_sub_u32 s1, s2, 208
	s_lshl_b32 s1, s1, 3
	s_add_u32 s3, s1, s0
	v_lshrrev_b32_e32 v200, 3, v202
	v_and_b32_e32 v201, 7, v202
	s_mul_i32 s4, s0, 4608
	v_mul_u32_u24_e32 v198, 0x240, v201
	v_lshl_add_u32 v198, v200, 2, v198
	v_add_u32_e32 v198, s4, v198
	v_mul_u32_u24_e32 v199, 0x90, v200
	v_lshl_add_u32 v199, v201, 4, v199
	v_add_u32_e32 v199, s4, v199
	v_lshlrev_b32_e32 v201, 4, v201
	s_mov_b32 s40, 0x43000000
	s_mov_b32 s41, 0x43000000
	v_readlane_b32 s10, v254, 38
	v_readlane_b32 s11, v254, 39
	v_readlane_b32 s12, v254, 2
	v_readlane_b32 s13, v254, 3
	v_readlane_b32 s94, v254, 4
	v_readlane_b32 s95, v254, 5
	s_mov_b32 s18, 0
	s_min_u32 s5, s3, 9215
	s_add_u32 s3, s3, 384
	s_cmp_lt_u32 s5, 0x400
	s_cbranch_scc1 .Lcp_m0_0
	s_cmp_lt_u32 s5, 0x1400
	s_cbranch_scc1 .Lcp_m1_0
	s_sub_u32 s5, s5, 0x1400
	s_and_b32 s1, s5, 63
	s_lshr_b32 s5, s5, 6
	s_mov_b32 s43, 13
	s_mov_b32 s55, 13
	s_mov_b64 s[6:7], s[94:95]
	s_add_u32 s8, s28, 0x4500000
	s_addc_u32 s9, s29, 0
	s_branch .Lcp_md_0

.Lcp_md_0:
	s_add_u32 s45, s43, 7
	s_lshl_b32 s53, s5, s45
	s_lshl_b32 s4, s1, 7
	s_add_u32 s53, s53, s4
	s_add_u32 s80, s6, s53
	s_addc_u32 s81, s7, 0
	s_add_u32 s45, s43, 5
	s_lshl_b32 s4, 1, s45
	s_add_u32 s82, s80, s4
	s_addc_u32 s83, s81, 0
	s_add_u32 s84, s82, s4
	s_addc_u32 s85, s83, 0
	s_add_u32 s86, s84, s4
	s_addc_u32 s87, s85, 0
	s_add_u32 s45, s55, 5
	s_lshl_b32 s4, s1, s45
	s_lshl_b32 s5, s5, 7
	s_add_u32 s4, s4, s5
	s_add_u32 s88, s8, s4
	s_addc_u32 s89, s9, 0
	s_add_u32 s45, s43, 2
	v_lshlrev_b32_e32 v194, s45, v200
	v_add_u32_e32 v194, v194, v201
	s_lshl_b32 s4, 1, s43
	v_add_u32_e32 v195, s4, v194
	v_add_u32_e32 v196, s4, v195
	v_add_u32_e32 v197, s4, v196
	global_load_dwordx4 v[0:3], v194, s[80:81]
	global_load_dwordx4 v[4:7], v195, s[80:81]
	global_load_dwordx4 v[8:11], v196, s[80:81]
	global_load_dwordx4 v[12:15], v197, s[80:81]
	global_load_dwordx4 v[16:19], v194, s[82:83]
	global_load_dwordx4 v[20:23], v195, s[82:83]
	global_load_dwordx4 v[24:27], v196, s[82:83]
	global_load_dwordx4 v[28:31], v197, s[82:83]
	global_load_dwordx4 v[32:35], v194, s[84:85]
	global_load_dwordx4 v[36:39], v195, s[84:85]
	global_load_dwordx4 v[40:43], v196, s[84:85]
	global_load_dwordx4 v[44:47], v197, s[84:85]
	global_load_dwordx4 v[48:51], v194, s[86:87]
	global_load_dwordx4 v[52:55], v195, s[86:87]
	global_load_dwordx4 v[56:59], v196, s[86:87]
	global_load_dwordx4 v[60:63], v197, s[86:87]
	s_min_u32 s5, s3, 9215
	s_add_u32 s3, s3, 384
	s_cmp_lt_u32 s5, 0x400
	s_cbranch_scc1 .Lcp_m0_1
	s_cmp_lt_u32 s5, 0x1400
	s_cbranch_scc1 .Lcp_m1_1
	s_sub_u32 s5, s5, 0x1400
	s_and_b32 s1, s5, 63
	s_lshr_b32 s5, s5, 6
	s_mov_b32 s43, 13
	s_mov_b32 s58, 13
	s_mov_b64 s[6:7], s[94:95]
	s_add_u32 s8, s28, 0x4500000
	s_addc_u32 s9, s29, 0
	s_branch .Lcp_md_1

.Lcp_md_1:
	s_add_u32 s45, s43, 7
	s_lshl_b32 s53, s5, s45
	s_lshl_b32 s4, s1, 7
	s_add_u32 s53, s53, s4
	s_add_u32 s80, s6, s53
	s_addc_u32 s81, s7, 0
	s_add_u32 s45, s43, 5
	s_lshl_b32 s4, 1, s45
	s_add_u32 s82, s80, s4
	s_addc_u32 s83, s81, 0
	s_add_u32 s84, s82, s4
	s_addc_u32 s85, s83, 0
	s_add_u32 s86, s84, s4
	s_addc_u32 s87, s85, 0
	s_add_u32 s45, s58, 5
	s_lshl_b32 s4, s1, s45
	s_lshl_b32 s5, s5, 7
	s_add_u32 s4, s4, s5
	s_add_u32 s90, s8, s4
	s_addc_u32 s91, s9, 0
	s_add_u32 s45, s43, 2
	v_lshlrev_b32_e32 v194, s45, v200
	v_add_u32_e32 v194, v194, v201
	s_lshl_b32 s4, 1, s43
	v_add_u32_e32 v195, s4, v194
	v_add_u32_e32 v196, s4, v195
	v_add_u32_e32 v197, s4, v196
	global_load_dwordx4 v[64:67], v194, s[80:81]
	global_load_dwordx4 v[68:71], v195, s[80:81]
	global_load_dwordx4 v[72:75], v196, s[80:81]
	global_load_dwordx4 v[76:79], v197, s[80:81]
	global_load_dwordx4 v[80:83], v194, s[82:83]
	global_load_dwordx4 v[84:87], v195, s[82:83]
	global_load_dwordx4 v[88:91], v196, s[82:83]
	global_load_dwordx4 v[92:95], v197, s[82:83]
	global_load_dwordx4 v[96:99], v194, s[84:85]
	global_load_dwordx4 v[100:103], v195, s[84:85]
	global_load_dwordx4 v[104:107], v196, s[84:85]
	global_load_dwordx4 v[108:111], v197, s[84:85]
	global_load_dwordx4 v[112:115], v194, s[86:87]
	global_load_dwordx4 v[116:119], v195, s[86:87]
	global_load_dwordx4 v[120:123], v196, s[86:87]
	global_load_dwordx4 v[124:127], v197, s[86:87]
	s_min_u32 s5, s3, 9215
	s_add_u32 s3, s3, 384
	s_cmp_lt_u32 s5, 0x400
	s_cbranch_scc1 .Lcp_m0_2
	s_cmp_lt_u32 s5, 0x1400
	s_cbranch_scc1 .Lcp_m1_2
	s_sub_u32 s5, s5, 0x1400
	s_and_b32 s1, s5, 63
	s_lshr_b32 s5, s5, 6
	s_mov_b32 s43, 13
	s_mov_b32 s59, 13
	s_mov_b64 s[6:7], s[94:95]
	s_add_u32 s8, s28, 0x4500000
	s_addc_u32 s9, s29, 0
	s_branch .Lcp_md_2

.Lcp_md_2:
	s_add_u32 s45, s43, 7
	s_lshl_b32 s53, s5, s45
	s_lshl_b32 s4, s1, 7
	s_add_u32 s53, s53, s4
	s_add_u32 s80, s6, s53
	s_addc_u32 s81, s7, 0
	s_add_u32 s45, s43, 5
	s_lshl_b32 s4, 1, s45
	s_add_u32 s82, s80, s4
	s_addc_u32 s83, s81, 0
	s_add_u32 s84, s82, s4
	s_addc_u32 s85, s83, 0
	s_add_u32 s86, s84, s4
	s_addc_u32 s87, s85, 0
	s_add_u32 s45, s59, 5
	s_lshl_b32 s4, s1, s45
	s_lshl_b32 s5, s5, 7
	s_add_u32 s4, s4, s5
	s_add_u32 s92, s8, s4
	s_addc_u32 s93, s9, 0
	s_add_u32 s45, s43, 2
	v_lshlrev_b32_e32 v194, s45, v200
	v_add_u32_e32 v194, v194, v201
	s_lshl_b32 s4, 1, s43
	v_add_u32_e32 v195, s4, v194
	v_add_u32_e32 v196, s4, v195
	v_add_u32_e32 v197, s4, v196
	global_load_dwordx4 v[128:131], v194, s[80:81]
	global_load_dwordx4 v[132:135], v195, s[80:81]
	global_load_dwordx4 v[136:139], v196, s[80:81]
	global_load_dwordx4 v[140:143], v197, s[80:81]
	global_load_dwordx4 v[144:147], v194, s[82:83]
	global_load_dwordx4 v[148:151], v195, s[82:83]
	global_load_dwordx4 v[152:155], v196, s[82:83]
	global_load_dwordx4 v[156:159], v197, s[82:83]
	global_load_dwordx4 v[160:163], v194, s[84:85]
	global_load_dwordx4 v[164:167], v195, s[84:85]
	global_load_dwordx4 v[168:171], v196, s[84:85]
	global_load_dwordx4 v[172:175], v197, s[84:85]
	global_load_dwordx4 v[176:179], v194, s[86:87]
	global_load_dwordx4 v[180:183], v195, s[86:87]
	global_load_dwordx4 v[186:189], v196, s[86:87]
	global_load_dwordx4 v[190:193], v197, s[86:87]
	s_waitcnt vmcnt(32)
	v_pk_mul_f32 v[0:1], v[0:1], s[40:41]
	v_pk_mul_f32 v[2:3], v[2:3], s[40:41]
	v_pk_mul_f32 v[4:5], v[4:5], s[40:41]
	v_pk_mul_f32 v[6:7], v[6:7], s[40:41]
	v_pk_mul_f32 v[8:9], v[8:9], s[40:41]
	v_pk_mul_f32 v[10:11], v[10:11], s[40:41]
	v_pk_mul_f32 v[12:13], v[12:13], s[40:41]
	v_pk_mul_f32 v[14:15], v[14:15], s[40:41]
	v_pk_mul_f32 v[16:17], v[16:17], s[40:41]
	v_pk_mul_f32 v[18:19], v[18:19], s[40:41]
	v_pk_mul_f32 v[20:21], v[20:21], s[40:41]
	v_pk_mul_f32 v[22:23], v[22:23], s[40:41]
	v_pk_mul_f32 v[24:25], v[24:25], s[40:41]
	v_pk_mul_f32 v[26:27], v[26:27], s[40:41]
	v_pk_mul_f32 v[28:29], v[28:29], s[40:41]
	v_pk_mul_f32 v[30:31], v[30:31], s[40:41]
	v_pk_mul_f32 v[32:33], v[32:33], s[40:41]
	v_pk_mul_f32 v[34:35], v[34:35], s[40:41]
	v_pk_mul_f32 v[36:37], v[36:37], s[40:41]
	v_pk_mul_f32 v[38:39], v[38:39], s[40:41]
	v_pk_mul_f32 v[40:41], v[40:41], s[40:41]
	v_pk_mul_f32 v[42:43], v[42:43], s[40:41]
	v_pk_mul_f32 v[44:45], v[44:45], s[40:41]
	v_pk_mul_f32 v[46:47], v[46:47], s[40:41]
	v_pk_mul_f32 v[48:49], v[48:49], s[40:41]
	v_pk_mul_f32 v[50:51], v[50:51], s[40:41]
	v_pk_mul_f32 v[52:53], v[52:53], s[40:41]
	v_pk_mul_f32 v[54:55], v[54:55], s[40:41]
	v_pk_mul_f32 v[56:57], v[56:57], s[40:41]
	v_pk_mul_f32 v[58:59], v[58:59], s[40:41]
	v_pk_mul_f32 v[60:61], v[60:61], s[40:41]
	v_pk_mul_f32 v[62:63], v[62:63], s[40:41]
	v_cvt_pk_fp8_f32 v0, v0, v4
	v_cvt_pk_fp8_f32 v1, v1, v5
	v_cvt_pk_fp8_f32 v2, v2, v6
	v_cvt_pk_fp8_f32 v3, v3, v7
	v_cvt_pk_fp8_f32 v0, v8, v12 op_sel:[0,0,1]
	v_cvt_pk_fp8_f32 v1, v9, v13 op_sel:[0,0,1]
	v_cvt_pk_fp8_f32 v2, v10, v14 op_sel:[0,0,1]
	v_cvt_pk_fp8_f32 v3, v11, v15 op_sel:[0,0,1]
	v_cvt_pk_fp8_f32 v16, v16, v20
	v_cvt_pk_fp8_f32 v17, v17, v21
	v_cvt_pk_fp8_f32 v18, v18, v22
	v_cvt_pk_fp8_f32 v19, v19, v23
	v_cvt_pk_fp8_f32 v16, v24, v28 op_sel:[0,0,1]
	v_cvt_pk_fp8_f32 v17, v25, v29 op_sel:[0,0,1]
	v_cvt_pk_fp8_f32 v18, v26, v30 op_sel:[0,0,1]
	v_cvt_pk_fp8_f32 v19, v27, v31 op_sel:[0,0,1]
	v_cvt_pk_fp8_f32 v32, v32, v36
	v_cvt_pk_fp8_f32 v33, v33, v37
	v_cvt_pk_fp8_f32 v34, v34, v38
	v_cvt_pk_fp8_f32 v35, v35, v39
	v_cvt_pk_fp8_f32 v32, v40, v44 op_sel:[0,0,1]
	v_cvt_pk_fp8_f32 v33, v41, v45 op_sel:[0,0,1]
	v_cvt_pk_fp8_f32 v34, v42, v46 op_sel:[0,0,1]
	v_cvt_pk_fp8_f32 v35, v43, v47 op_sel:[0,0,1]
	v_cvt_pk_fp8_f32 v48, v48, v52
	v_cvt_pk_fp8_f32 v49, v49, v53
	v_cvt_pk_fp8_f32 v50, v50, v54
	v_cvt_pk_fp8_f32 v51, v51, v55
	v_cvt_pk_fp8_f32 v48, v56, v60 op_sel:[0,0,1]
	v_cvt_pk_fp8_f32 v49, v57, v61 op_sel:[0,0,1]
	v_cvt_pk_fp8_f32 v50, v58, v62 op_sel:[0,0,1]
	v_cvt_pk_fp8_f32 v51, v59, v63 op_sel:[0,0,1]
	s_nop 0
	ds_write2_b32 v198, v0, v16 offset0:0 offset1:8
	ds_write2_b32 v198, v32, v48 offset0:16 offset1:24
	ds_write2_b32 v198, v1, v17 offset0:36 offset1:44
	ds_write2_b32 v198, v33, v49 offset0:52 offset1:60
	ds_write2_b32 v198, v2, v18 offset0:72 offset1:80
	ds_write2_b32 v198, v34, v50 offset0:88 offset1:96
	ds_write2_b32 v198, v3, v19 offset0:108 offset1:116
	ds_write2_b32 v198, v35, v51 offset0:124 offset1:132
	v_lshlrev_b32_e32 v8, s55, v200
	v_add_u32_e32 v8, v8, v201
	s_add_u32 s45, s55, 3
	s_lshl_b32 s4, 1, s45
	v_add_u32_e32 v24, s4, v8
	v_add_u32_e32 v40, s4, v24
	v_add_u32_e32 v56, s4, v40
	s_waitcnt lgkmcnt(0)
	ds_read_b128 v[4:7], v199 offset:0
	ds_read_b128 v[20:23], v199 offset:1152
	ds_read_b128 v[36:39], v199 offset:2304
	ds_read_b128 v[52:55], v199 offset:3456
	s_waitcnt lgkmcnt(3)
	global_store_dwordx4 v8, v[4:7], s[88:89]
	s_waitcnt lgkmcnt(2)
	global_store_dwordx4 v24, v[20:23], s[88:89]
	s_waitcnt lgkmcnt(1)
	global_store_dwordx4 v40, v[36:39], s[88:89]
	s_waitcnt lgkmcnt(0)
	global_store_dwordx4 v56, v[52:55], s[88:89]
	s_min_u32 s5, s3, 9215
	s_add_u32 s3, s3, 384
	s_cmp_lt_u32 s5, 0x400
	s_cbranch_scc1 .Lcp_m0_3
	s_cmp_lt_u32 s5, 0x1400
	s_cbranch_scc1 .Lcp_m1_3
	s_sub_u32 s5, s5, 0x1400
	s_and_b32 s1, s5, 63
	s_lshr_b32 s5, s5, 6
	s_mov_b32 s43, 13
	s_mov_b32 s55, 13
	s_mov_b64 s[6:7], s[94:95]
	s_add_u32 s8, s28, 0x4500000
	s_addc_u32 s9, s29, 0
	s_branch .Lcp_md_3

.Lcp_md_3:
	s_add_u32 s45, s43, 7
	s_lshl_b32 s53, s5, s45
	s_lshl_b32 s4, s1, 7
	s_add_u32 s53, s53, s4
	s_add_u32 s80, s6, s53
	s_addc_u32 s81, s7, 0
	s_add_u32 s45, s43, 5
	s_lshl_b32 s4, 1, s45
	s_add_u32 s82, s80, s4
	s_addc_u32 s83, s81, 0
	s_add_u32 s84, s82, s4
	s_addc_u32 s85, s83, 0
	s_add_u32 s86, s84, s4
	s_addc_u32 s87, s85, 0
	s_add_u32 s45, s55, 5
	s_lshl_b32 s4, s1, s45
	s_lshl_b32 s5, s5, 7
	s_add_u32 s4, s4, s5
	s_add_u32 s88, s8, s4
	s_addc_u32 s89, s9, 0
	s_add_u32 s45, s43, 2
	v_lshlrev_b32_e32 v194, s45, v200
	v_add_u32_e32 v194, v194, v201
	s_lshl_b32 s4, 1, s43
	v_add_u32_e32 v195, s4, v194
	v_add_u32_e32 v196, s4, v195
	v_add_u32_e32 v197, s4, v196
	global_load_dwordx4 v[0:3], v194, s[80:81]
	global_load_dwordx4 v[4:7], v195, s[80:81]
	global_load_dwordx4 v[8:11], v196, s[80:81]
	global_load_dwordx4 v[12:15], v197, s[80:81]
	global_load_dwordx4 v[16:19], v194, s[82:83]
	global_load_dwordx4 v[20:23], v195, s[82:83]
	global_load_dwordx4 v[24:27], v196, s[82:83]
	global_load_dwordx4 v[28:31], v197, s[82:83]
	global_load_dwordx4 v[32:35], v194, s[84:85]
	global_load_dwordx4 v[36:39], v195, s[84:85]
	global_load_dwordx4 v[40:43], v196, s[84:85]
	global_load_dwordx4 v[44:47], v197, s[84:85]
	global_load_dwordx4 v[48:51], v194, s[86:87]
	global_load_dwordx4 v[52:55], v195, s[86:87]
	global_load_dwordx4 v[56:59], v196, s[86:87]
	global_load_dwordx4 v[60:63], v197, s[86:87]
	s_waitcnt vmcnt(36)
	v_pk_mul_f32 v[64:65], v[64:65], s[40:41]
	v_pk_mul_f32 v[66:67], v[66:67], s[40:41]
	v_pk_mul_f32 v[68:69], v[68:69], s[40:41]
	v_pk_mul_f32 v[70:71], v[70:71], s[40:41]
	v_pk_mul_f32 v[72:73], v[72:73], s[40:41]
	v_pk_mul_f32 v[74:75], v[74:75], s[40:41]
	v_pk_mul_f32 v[76:77], v[76:77], s[40:41]
	v_pk_mul_f32 v[78:79], v[78:79], s[40:41]
	v_pk_mul_f32 v[80:81], v[80:81], s[40:41]
	v_pk_mul_f32 v[82:83], v[82:83], s[40:41]
	v_pk_mul_f32 v[84:85], v[84:85], s[40:41]
	v_pk_mul_f32 v[86:87], v[86:87], s[40:41]
	v_pk_mul_f32 v[88:89], v[88:89], s[40:41]
	v_pk_mul_f32 v[90:91], v[90:91], s[40:41]
	v_pk_mul_f32 v[92:93], v[92:93], s[40:41]
	v_pk_mul_f32 v[94:95], v[94:95], s[40:41]
	v_pk_mul_f32 v[96:97], v[96:97], s[40:41]
	v_pk_mul_f32 v[98:99], v[98:99], s[40:41]
	v_pk_mul_f32 v[100:101], v[100:101], s[40:41]
	v_pk_mul_f32 v[102:103], v[102:103], s[40:41]
	v_pk_mul_f32 v[104:105], v[104:105], s[40:41]
	v_pk_mul_f32 v[106:107], v[106:107], s[40:41]
	v_pk_mul_f32 v[108:109], v[108:109], s[40:41]
	v_pk_mul_f32 v[110:111], v[110:111], s[40:41]
	v_pk_mul_f32 v[112:113], v[112:113], s[40:41]
	v_pk_mul_f32 v[114:115], v[114:115], s[40:41]
	v_pk_mul_f32 v[116:117], v[116:117], s[40:41]
	v_pk_mul_f32 v[118:119], v[118:119], s[40:41]
	v_pk_mul_f32 v[120:121], v[120:121], s[40:41]
	v_pk_mul_f32 v[122:123], v[122:123], s[40:41]
	v_pk_mul_f32 v[124:125], v[124:125], s[40:41]
	v_pk_mul_f32 v[126:127], v[126:127], s[40:41]
	v_cvt_pk_fp8_f32 v64, v64, v68
	v_cvt_pk_fp8_f32 v65, v65, v69
	v_cvt_pk_fp8_f32 v66, v66, v70
	v_cvt_pk_fp8_f32 v67, v67, v71
	v_cvt_pk_fp8_f32 v64, v72, v76 op_sel:[0,0,1]
	v_cvt_pk_fp8_f32 v65, v73, v77 op_sel:[0,0,1]
	v_cvt_pk_fp8_f32 v66, v74, v78 op_sel:[0,0,1]
	v_cvt_pk_fp8_f32 v67, v75, v79 op_sel:[0,0,1]
	v_cvt_pk_fp8_f32 v80, v80, v84
	v_cvt_pk_fp8_f32 v81, v81, v85
	v_cvt_pk_fp8_f32 v82, v82, v86
	v_cvt_pk_fp8_f32 v83, v83, v87
	v_cvt_pk_fp8_f32 v80, v88, v92 op_sel:[0,0,1]
	v_cvt_pk_fp8_f32 v81, v89, v93 op_sel:[0,0,1]
	v_cvt_pk_fp8_f32 v82, v90, v94 op_sel:[0,0,1]
	v_cvt_pk_fp8_f32 v83, v91, v95 op_sel:[0,0,1]
	v_cvt_pk_fp8_f32 v96, v96, v100
	v_cvt_pk_fp8_f32 v97, v97, v101
	v_cvt_pk_fp8_f32 v98, v98, v102
	v_cvt_pk_fp8_f32 v99, v99, v103
	v_cvt_pk_fp8_f32 v96, v104, v108 op_sel:[0,0,1]
	v_cvt_pk_fp8_f32 v97, v105, v109 op_sel:[0,0,1]
	v_cvt_pk_fp8_f32 v98, v106, v110 op_sel:[0,0,1]
	v_cvt_pk_fp8_f32 v99, v107, v111 op_sel:[0,0,1]
	v_cvt_pk_fp8_f32 v112, v112, v116
	v_cvt_pk_fp8_f32 v113, v113, v117
	v_cvt_pk_fp8_f32 v114, v114, v118
	v_cvt_pk_fp8_f32 v115, v115, v119
	v_cvt_pk_fp8_f32 v112, v120, v124 op_sel:[0,0,1]
	v_cvt_pk_fp8_f32 v113, v121, v125 op_sel:[0,0,1]
	v_cvt_pk_fp8_f32 v114, v122, v126 op_sel:[0,0,1]
	v_cvt_pk_fp8_f32 v115, v123, v127 op_sel:[0,0,1]
	s_nop 0
	ds_write2_b32 v198, v64, v80 offset0:0 offset1:8
	ds_write2_b32 v198, v96, v112 offset0:16 offset1:24
	ds_write2_b32 v198, v65, v81 offset0:36 offset1:44
	ds_write2_b32 v198, v97, v113 offset0:52 offset1:60
	ds_write2_b32 v198, v66, v82 offset0:72 offset1:80
	ds_write2_b32 v198, v98, v114 offset0:88 offset1:96
	ds_write2_b32 v198, v67, v83 offset0:108 offset1:116
	ds_write2_b32 v198, v99, v115 offset0:124 offset1:132
	v_lshlrev_b32_e32 v72, s58, v200
	v_add_u32_e32 v72, v72, v201
	s_add_u32 s45, s58, 3
	s_lshl_b32 s4, 1, s45
	v_add_u32_e32 v88, s4, v72
	v_add_u32_e32 v104, s4, v88
	v_add_u32_e32 v120, s4, v104
	s_waitcnt lgkmcnt(0)
	ds_read_b128 v[68:71], v199 offset:0
	ds_read_b128 v[84:87], v199 offset:1152
	ds_read_b128 v[100:103], v199 offset:2304
	ds_read_b128 v[116:119], v199 offset:3456
	s_waitcnt lgkmcnt(3)
	global_store_dwordx4 v72, v[68:71], s[90:91]
	s_waitcnt lgkmcnt(2)
	global_store_dwordx4 v88, v[84:87], s[90:91]
	s_waitcnt lgkmcnt(1)
	global_store_dwordx4 v104, v[100:103], s[90:91]
	s_waitcnt lgkmcnt(0)
	global_store_dwordx4 v120, v[116:119], s[90:91]
	s_min_u32 s5, s3, 9215
	s_add_u32 s3, s3, 384
	s_cmp_lt_u32 s5, 0x400
	s_cbranch_scc1 .Lcp_m0_4
	s_cmp_lt_u32 s5, 0x1400
	s_cbranch_scc1 .Lcp_m1_4
	s_sub_u32 s5, s5, 0x1400
	s_and_b32 s1, s5, 63
	s_lshr_b32 s5, s5, 6
	s_mov_b32 s43, 13
	s_mov_b32 s58, 13
	s_mov_b64 s[6:7], s[94:95]
	s_add_u32 s8, s28, 0x4500000
	s_addc_u32 s9, s29, 0
	s_branch .Lcp_md_4

.Lcp_loop:
	s_min_u32 s5, s3, 9215
	s_add_u32 s3, s3, 384
	s_cmp_lt_u32 s5, 0x400
	s_cbranch_scc1 .Lcp_m0_5
	s_cmp_lt_u32 s5, 0x1400
	s_cbranch_scc1 .Lcp_m1_5
	s_sub_u32 s5, s5, 0x1400
	s_and_b32 s1, s5, 63
	s_lshr_b32 s5, s5, 6
	s_mov_b32 s43, 13
	s_mov_b32 s59, 13
	s_mov_b64 s[6:7], s[94:95]
	s_add_u32 s8, s28, 0x4500000
	s_addc_u32 s9, s29, 0
	s_branch .Lcp_md_5

.Lcp_md_5:
	s_add_u32 s45, s43, 7
	s_lshl_b32 s53, s5, s45
	s_lshl_b32 s4, s1, 7
	s_add_u32 s53, s53, s4
	s_add_u32 s80, s6, s53
	s_addc_u32 s81, s7, 0
	s_add_u32 s45, s43, 5
	s_lshl_b32 s4, 1, s45
	s_add_u32 s82, s80, s4
	s_addc_u32 s83, s81, 0
	s_add_u32 s84, s82, s4
	s_addc_u32 s85, s83, 0
	s_add_u32 s86, s84, s4
	s_addc_u32 s87, s85, 0
	s_add_u32 s45, s59, 5
	s_lshl_b32 s4, s1, s45
	s_lshl_b32 s5, s5, 7
	s_add_u32 s4, s4, s5
	s_add_u32 s92, s8, s4
	s_addc_u32 s93, s9, 0
	s_add_u32 s45, s43, 2
	v_lshlrev_b32_e32 v194, s45, v200
	v_add_u32_e32 v194, v194, v201
	s_lshl_b32 s4, 1, s43
	v_add_u32_e32 v195, s4, v194
	v_add_u32_e32 v196, s4, v195
	v_add_u32_e32 v197, s4, v196
	global_load_dwordx4 v[128:131], v194, s[80:81]
	global_load_dwordx4 v[132:135], v195, s[80:81]
	global_load_dwordx4 v[136:139], v196, s[80:81]
	global_load_dwordx4 v[140:143], v197, s[80:81]
	global_load_dwordx4 v[144:147], v194, s[82:83]
	global_load_dwordx4 v[148:151], v195, s[82:83]
	global_load_dwordx4 v[152:155], v196, s[82:83]
	global_load_dwordx4 v[156:159], v197, s[82:83]
	global_load_dwordx4 v[160:163], v194, s[84:85]
	global_load_dwordx4 v[164:167], v195, s[84:85]
	global_load_dwordx4 v[168:171], v196, s[84:85]
	global_load_dwordx4 v[172:175], v197, s[84:85]
	global_load_dwordx4 v[176:179], v194, s[86:87]
	global_load_dwordx4 v[180:183], v195, s[86:87]
	global_load_dwordx4 v[186:189], v196, s[86:87]
	global_load_dwordx4 v[190:193], v197, s[86:87]
	s_waitcnt vmcnt(40)
	v_pk_mul_f32 v[0:1], v[0:1], s[40:41]
	v_pk_mul_f32 v[2:3], v[2:3], s[40:41]
	v_pk_mul_f32 v[4:5], v[4:5], s[40:41]
	v_pk_mul_f32 v[6:7], v[6:7], s[40:41]
	v_pk_mul_f32 v[8:9], v[8:9], s[40:41]
	v_pk_mul_f32 v[10:11], v[10:11], s[40:41]
	v_pk_mul_f32 v[12:13], v[12:13], s[40:41]
	v_pk_mul_f32 v[14:15], v[14:15], s[40:41]
	v_pk_mul_f32 v[16:17], v[16:17], s[40:41]
	v_pk_mul_f32 v[18:19], v[18:19], s[40:41]
	v_pk_mul_f32 v[20:21], v[20:21], s[40:41]
	v_pk_mul_f32 v[22:23], v[22:23], s[40:41]
	v_pk_mul_f32 v[24:25], v[24:25], s[40:41]
	v_pk_mul_f32 v[26:27], v[26:27], s[40:41]
	v_pk_mul_f32 v[28:29], v[28:29], s[40:41]
	v_pk_mul_f32 v[30:31], v[30:31], s[40:41]
	v_pk_mul_f32 v[32:33], v[32:33], s[40:41]
	v_pk_mul_f32 v[34:35], v[34:35], s[40:41]
	v_pk_mul_f32 v[36:37], v[36:37], s[40:41]
	v_pk_mul_f32 v[38:39], v[38:39], s[40:41]
	v_pk_mul_f32 v[40:41], v[40:41], s[40:41]
	v_pk_mul_f32 v[42:43], v[42:43], s[40:41]
	v_pk_mul_f32 v[44:45], v[44:45], s[40:41]
	v_pk_mul_f32 v[46:47], v[46:47], s[40:41]
	v_pk_mul_f32 v[48:49], v[48:49], s[40:41]
	v_pk_mul_f32 v[50:51], v[50:51], s[40:41]
	v_pk_mul_f32 v[52:53], v[52:53], s[40:41]
	v_pk_mul_f32 v[54:55], v[54:55], s[40:41]
	v_pk_mul_f32 v[56:57], v[56:57], s[40:41]
	v_pk_mul_f32 v[58:59], v[58:59], s[40:41]
	v_pk_mul_f32 v[60:61], v[60:61], s[40:41]
	v_pk_mul_f32 v[62:63], v[62:63], s[40:41]
	v_cvt_pk_fp8_f32 v0, v0, v4
	v_cvt_pk_fp8_f32 v1, v1, v5
	v_cvt_pk_fp8_f32 v2, v2, v6
	v_cvt_pk_fp8_f32 v3, v3, v7
	v_cvt_pk_fp8_f32 v0, v8, v12 op_sel:[0,0,1]
	v_cvt_pk_fp8_f32 v1, v9, v13 op_sel:[0,0,1]
	v_cvt_pk_fp8_f32 v2, v10, v14 op_sel:[0,0,1]
	v_cvt_pk_fp8_f32 v3, v11, v15 op_sel:[0,0,1]
	v_cvt_pk_fp8_f32 v16, v16, v20
	v_cvt_pk_fp8_f32 v17, v17, v21
	v_cvt_pk_fp8_f32 v18, v18, v22
	v_cvt_pk_fp8_f32 v19, v19, v23
	v_cvt_pk_fp8_f32 v16, v24, v28 op_sel:[0,0,1]
	v_cvt_pk_fp8_f32 v17, v25, v29 op_sel:[0,0,1]
	v_cvt_pk_fp8_f32 v18, v26, v30 op_sel:[0,0,1]
	v_cvt_pk_fp8_f32 v19, v27, v31 op_sel:[0,0,1]
	v_cvt_pk_fp8_f32 v32, v32, v36
	v_cvt_pk_fp8_f32 v33, v33, v37
	v_cvt_pk_fp8_f32 v34, v34, v38
	v_cvt_pk_fp8_f32 v35, v35, v39
	v_cvt_pk_fp8_f32 v32, v40, v44 op_sel:[0,0,1]
	v_cvt_pk_fp8_f32 v33, v41, v45 op_sel:[0,0,1]
	v_cvt_pk_fp8_f32 v34, v42, v46 op_sel:[0,0,1]
	v_cvt_pk_fp8_f32 v35, v43, v47 op_sel:[0,0,1]
	v_cvt_pk_fp8_f32 v48, v48, v52
	v_cvt_pk_fp8_f32 v49, v49, v53
	v_cvt_pk_fp8_f32 v50, v50, v54
	v_cvt_pk_fp8_f32 v51, v51, v55
	v_cvt_pk_fp8_f32 v48, v56, v60 op_sel:[0,0,1]
	v_cvt_pk_fp8_f32 v49, v57, v61 op_sel:[0,0,1]
	v_cvt_pk_fp8_f32 v50, v58, v62 op_sel:[0,0,1]
	v_cvt_pk_fp8_f32 v51, v59, v63 op_sel:[0,0,1]
	s_nop 0
	ds_write2_b32 v198, v0, v16 offset0:0 offset1:8
	ds_write2_b32 v198, v32, v48 offset0:16 offset1:24
	ds_write2_b32 v198, v1, v17 offset0:36 offset1:44
	ds_write2_b32 v198, v33, v49 offset0:52 offset1:60
	ds_write2_b32 v198, v2, v18 offset0:72 offset1:80
	ds_write2_b32 v198, v34, v50 offset0:88 offset1:96
	ds_write2_b32 v198, v3, v19 offset0:108 offset1:116
	ds_write2_b32 v198, v35, v51 offset0:124 offset1:132
	v_lshlrev_b32_e32 v8, s55, v200
	v_add_u32_e32 v8, v8, v201
	s_add_u32 s45, s55, 3
	s_lshl_b32 s4, 1, s45
	v_add_u32_e32 v24, s4, v8
	v_add_u32_e32 v40, s4, v24
	v_add_u32_e32 v56, s4, v40
	s_waitcnt lgkmcnt(0)
	ds_read_b128 v[4:7], v199 offset:0
	ds_read_b128 v[20:23], v199 offset:1152
	ds_read_b128 v[36:39], v199 offset:2304
	ds_read_b128 v[52:55], v199 offset:3456
	s_waitcnt lgkmcnt(3)
	global_store_dwordx4 v8, v[4:7], s[88:89]
	s_waitcnt lgkmcnt(2)
	global_store_dwordx4 v24, v[20:23], s[88:89]
	s_waitcnt lgkmcnt(1)
	global_store_dwordx4 v40, v[36:39], s[88:89]
	s_waitcnt lgkmcnt(0)
	global_store_dwordx4 v56, v[52:55], s[88:89]
	s_min_u32 s5, s3, 9215
	s_add_u32 s3, s3, 384
	s_cmp_lt_u32 s5, 0x400
	s_cbranch_scc1 .Lcp_m0_6
	s_cmp_lt_u32 s5, 0x1400
	s_cbranch_scc1 .Lcp_m1_6
	s_sub_u32 s5, s5, 0x1400
	s_and_b32 s1, s5, 63
	s_lshr_b32 s5, s5, 6
	s_mov_b32 s43, 13
	s_mov_b32 s55, 13
	s_mov_b64 s[6:7], s[94:95]
	s_add_u32 s8, s28, 0x4500000
	s_addc_u32 s9, s29, 0
	s_branch .Lcp_md_6

.Lcp_md_6:
	s_add_u32 s45, s43, 7
	s_lshl_b32 s53, s5, s45
	s_lshl_b32 s4, s1, 7
	s_add_u32 s53, s53, s4
	s_add_u32 s80, s6, s53
	s_addc_u32 s81, s7, 0
	s_add_u32 s45, s43, 5
	s_lshl_b32 s4, 1, s45
	s_add_u32 s82, s80, s4
	s_addc_u32 s83, s81, 0
	s_add_u32 s84, s82, s4
	s_addc_u32 s85, s83, 0
	s_add_u32 s86, s84, s4
	s_addc_u32 s87, s85, 0
	s_add_u32 s45, s55, 5
	s_lshl_b32 s4, s1, s45
	s_lshl_b32 s5, s5, 7
	s_add_u32 s4, s4, s5
	s_add_u32 s88, s8, s4
	s_addc_u32 s89, s9, 0
	s_add_u32 s45, s43, 2
	v_lshlrev_b32_e32 v194, s45, v200
	v_add_u32_e32 v194, v194, v201
	s_lshl_b32 s4, 1, s43
	v_add_u32_e32 v195, s4, v194
	v_add_u32_e32 v196, s4, v195
	v_add_u32_e32 v197, s4, v196
	global_load_dwordx4 v[0:3], v194, s[80:81]
	global_load_dwordx4 v[4:7], v195, s[80:81]
	global_load_dwordx4 v[8:11], v196, s[80:81]
	global_load_dwordx4 v[12:15], v197, s[80:81]
	global_load_dwordx4 v[16:19], v194, s[82:83]
	global_load_dwordx4 v[20:23], v195, s[82:83]
	global_load_dwordx4 v[24:27], v196, s[82:83]
	global_load_dwordx4 v[28:31], v197, s[82:83]
	global_load_dwordx4 v[32:35], v194, s[84:85]
	global_load_dwordx4 v[36:39], v195, s[84:85]
	global_load_dwordx4 v[40:43], v196, s[84:85]
	global_load_dwordx4 v[44:47], v197, s[84:85]
	global_load_dwordx4 v[48:51], v194, s[86:87]
	global_load_dwordx4 v[52:55], v195, s[86:87]
	global_load_dwordx4 v[56:59], v196, s[86:87]
	global_load_dwordx4 v[60:63], v197, s[86:87]
	s_waitcnt vmcnt(40)
	v_pk_mul_f32 v[64:65], v[64:65], s[40:41]
	v_pk_mul_f32 v[66:67], v[66:67], s[40:41]
	v_pk_mul_f32 v[68:69], v[68:69], s[40:41]
	v_pk_mul_f32 v[70:71], v[70:71], s[40:41]
	v_pk_mul_f32 v[72:73], v[72:73], s[40:41]
	v_pk_mul_f32 v[74:75], v[74:75], s[40:41]
	v_pk_mul_f32 v[76:77], v[76:77], s[40:41]
	v_pk_mul_f32 v[78:79], v[78:79], s[40:41]
	v_pk_mul_f32 v[80:81], v[80:81], s[40:41]
	v_pk_mul_f32 v[82:83], v[82:83], s[40:41]
	v_pk_mul_f32 v[84:85], v[84:85], s[40:41]
	v_pk_mul_f32 v[86:87], v[86:87], s[40:41]
	v_pk_mul_f32 v[88:89], v[88:89], s[40:41]
	v_pk_mul_f32 v[90:91], v[90:91], s[40:41]
	v_pk_mul_f32 v[92:93], v[92:93], s[40:41]
	v_pk_mul_f32 v[94:95], v[94:95], s[40:41]
	v_pk_mul_f32 v[96:97], v[96:97], s[40:41]
	v_pk_mul_f32 v[98:99], v[98:99], s[40:41]
	v_pk_mul_f32 v[100:101], v[100:101], s[40:41]
	v_pk_mul_f32 v[102:103], v[102:103], s[40:41]
	v_pk_mul_f32 v[104:105], v[104:105], s[40:41]
	v_pk_mul_f32 v[106:107], v[106:107], s[40:41]
	v_pk_mul_f32 v[108:109], v[108:109], s[40:41]
	v_pk_mul_f32 v[110:111], v[110:111], s[40:41]
	v_pk_mul_f32 v[112:113], v[112:113], s[40:41]
	v_pk_mul_f32 v[114:115], v[114:115], s[40:41]
	v_pk_mul_f32 v[116:117], v[116:117], s[40:41]
	v_pk_mul_f32 v[118:119], v[118:119], s[40:41]
	v_pk_mul_f32 v[120:121], v[120:121], s[40:41]
	v_pk_mul_f32 v[122:123], v[122:123], s[40:41]
	v_pk_mul_f32 v[124:125], v[124:125], s[40:41]
	v_pk_mul_f32 v[126:127], v[126:127], s[40:41]
	v_cvt_pk_fp8_f32 v64, v64, v68
	v_cvt_pk_fp8_f32 v65, v65, v69
	v_cvt_pk_fp8_f32 v66, v66, v70
	v_cvt_pk_fp8_f32 v67, v67, v71
	v_cvt_pk_fp8_f32 v64, v72, v76 op_sel:[0,0,1]
	v_cvt_pk_fp8_f32 v65, v73, v77 op_sel:[0,0,1]
	v_cvt_pk_fp8_f32 v66, v74, v78 op_sel:[0,0,1]
	v_cvt_pk_fp8_f32 v67, v75, v79 op_sel:[0,0,1]
	v_cvt_pk_fp8_f32 v80, v80, v84
	v_cvt_pk_fp8_f32 v81, v81, v85
	v_cvt_pk_fp8_f32 v82, v82, v86
	v_cvt_pk_fp8_f32 v83, v83, v87
	v_cvt_pk_fp8_f32 v80, v88, v92 op_sel:[0,0,1]
	v_cvt_pk_fp8_f32 v81, v89, v93 op_sel:[0,0,1]
	v_cvt_pk_fp8_f32 v82, v90, v94 op_sel:[0,0,1]
	v_cvt_pk_fp8_f32 v83, v91, v95 op_sel:[0,0,1]
	v_cvt_pk_fp8_f32 v96, v96, v100
	v_cvt_pk_fp8_f32 v97, v97, v101
	v_cvt_pk_fp8_f32 v98, v98, v102
	v_cvt_pk_fp8_f32 v99, v99, v103
	v_cvt_pk_fp8_f32 v96, v104, v108 op_sel:[0,0,1]
	v_cvt_pk_fp8_f32 v97, v105, v109 op_sel:[0,0,1]
	v_cvt_pk_fp8_f32 v98, v106, v110 op_sel:[0,0,1]
	v_cvt_pk_fp8_f32 v99, v107, v111 op_sel:[0,0,1]
	v_cvt_pk_fp8_f32 v112, v112, v116
	v_cvt_pk_fp8_f32 v113, v113, v117
	v_cvt_pk_fp8_f32 v114, v114, v118
	v_cvt_pk_fp8_f32 v115, v115, v119
	v_cvt_pk_fp8_f32 v112, v120, v124 op_sel:[0,0,1]
	v_cvt_pk_fp8_f32 v113, v121, v125 op_sel:[0,0,1]
	v_cvt_pk_fp8_f32 v114, v122, v126 op_sel:[0,0,1]
	v_cvt_pk_fp8_f32 v115, v123, v127 op_sel:[0,0,1]
	s_nop 0
	ds_write2_b32 v198, v64, v80 offset0:0 offset1:8
	ds_write2_b32 v198, v96, v112 offset0:16 offset1:24
	ds_write2_b32 v198, v65, v81 offset0:36 offset1:44
	ds_write2_b32 v198, v97, v113 offset0:52 offset1:60
	ds_write2_b32 v198, v66, v82 offset0:72 offset1:80
	ds_write2_b32 v198, v98, v114 offset0:88 offset1:96
	ds_write2_b32 v198, v67, v83 offset0:108 offset1:116
	ds_write2_b32 v198, v99, v115 offset0:124 offset1:132
	v_lshlrev_b32_e32 v72, s58, v200
	v_add_u32_e32 v72, v72, v201
	s_add_u32 s45, s58, 3
	s_lshl_b32 s4, 1, s45
	v_add_u32_e32 v88, s4, v72
	v_add_u32_e32 v104, s4, v88
	v_add_u32_e32 v120, s4, v104
	s_waitcnt lgkmcnt(0)
	ds_read_b128 v[68:71], v199 offset:0
	ds_read_b128 v[84:87], v199 offset:1152
	ds_read_b128 v[100:103], v199 offset:2304
	ds_read_b128 v[116:119], v199 offset:3456
	s_waitcnt lgkmcnt(3)
	global_store_dwordx4 v72, v[68:71], s[90:91]
	s_waitcnt lgkmcnt(2)
	global_store_dwordx4 v88, v[84:87], s[90:91]
	s_waitcnt lgkmcnt(1)
	global_store_dwordx4 v104, v[100:103], s[90:91]
	s_waitcnt lgkmcnt(0)
	global_store_dwordx4 v120, v[116:119], s[90:91]
	s_min_u32 s5, s3, 9215
	s_add_u32 s3, s3, 384
	s_cmp_lt_u32 s5, 0x400
	s_cbranch_scc1 .Lcp_m0_7
	s_cmp_lt_u32 s5, 0x1400
	s_cbranch_scc1 .Lcp_m1_7
	s_sub_u32 s5, s5, 0x1400
	s_and_b32 s1, s5, 63
	s_lshr_b32 s5, s5, 6
	s_mov_b32 s43, 13
	s_mov_b32 s58, 13
	s_mov_b64 s[6:7], s[94:95]
	s_add_u32 s8, s28, 0x4500000
	s_addc_u32 s9, s29, 0
	s_branch .Lcp_md_7

.Lcp_md_7:
	s_add_u32 s45, s43, 7
	s_lshl_b32 s53, s5, s45
	s_lshl_b32 s4, s1, 7
	s_add_u32 s53, s53, s4
	s_add_u32 s80, s6, s53
	s_addc_u32 s81, s7, 0
	s_add_u32 s45, s43, 5
	s_lshl_b32 s4, 1, s45
	s_add_u32 s82, s80, s4
	s_addc_u32 s83, s81, 0
	s_add_u32 s84, s82, s4
	s_addc_u32 s85, s83, 0
	s_add_u32 s86, s84, s4
	s_addc_u32 s87, s85, 0
	s_add_u32 s45, s58, 5
	s_lshl_b32 s4, s1, s45
	s_lshl_b32 s5, s5, 7
	s_add_u32 s4, s4, s5
	s_add_u32 s90, s8, s4
	s_addc_u32 s91, s9, 0
	s_add_u32 s45, s43, 2
	v_lshlrev_b32_e32 v194, s45, v200
	v_add_u32_e32 v194, v194, v201
	s_lshl_b32 s4, 1, s43
	v_add_u32_e32 v195, s4, v194
	v_add_u32_e32 v196, s4, v195
	v_add_u32_e32 v197, s4, v196
	global_load_dwordx4 v[64:67], v194, s[80:81]
	global_load_dwordx4 v[68:71], v195, s[80:81]
	global_load_dwordx4 v[72:75], v196, s[80:81]
	global_load_dwordx4 v[76:79], v197, s[80:81]
	global_load_dwordx4 v[80:83], v194, s[82:83]
	global_load_dwordx4 v[84:87], v195, s[82:83]
	global_load_dwordx4 v[88:91], v196, s[82:83]
	global_load_dwordx4 v[92:95], v197, s[82:83]
	global_load_dwordx4 v[96:99], v194, s[84:85]
	global_load_dwordx4 v[100:103], v195, s[84:85]
	global_load_dwordx4 v[104:107], v196, s[84:85]
	global_load_dwordx4 v[108:111], v197, s[84:85]
	global_load_dwordx4 v[112:115], v194, s[86:87]
	global_load_dwordx4 v[116:119], v195, s[86:87]
	global_load_dwordx4 v[120:123], v196, s[86:87]
	global_load_dwordx4 v[124:127], v197, s[86:87]
	s_waitcnt vmcnt(40)
	v_pk_mul_f32 v[128:129], v[128:129], s[40:41]
	v_pk_mul_f32 v[130:131], v[130:131], s[40:41]
	v_pk_mul_f32 v[132:133], v[132:133], s[40:41]
	v_pk_mul_f32 v[134:135], v[134:135], s[40:41]
	v_pk_mul_f32 v[136:137], v[136:137], s[40:41]
	v_pk_mul_f32 v[138:139], v[138:139], s[40:41]
	v_pk_mul_f32 v[140:141], v[140:141], s[40:41]
	v_pk_mul_f32 v[142:143], v[142:143], s[40:41]
	v_pk_mul_f32 v[144:145], v[144:145], s[40:41]
	v_pk_mul_f32 v[146:147], v[146:147], s[40:41]
	v_pk_mul_f32 v[148:149], v[148:149], s[40:41]
	v_pk_mul_f32 v[150:151], v[150:151], s[40:41]
	v_pk_mul_f32 v[152:153], v[152:153], s[40:41]
	v_pk_mul_f32 v[154:155], v[154:155], s[40:41]
	v_pk_mul_f32 v[156:157], v[156:157], s[40:41]
	v_pk_mul_f32 v[158:159], v[158:159], s[40:41]
	v_pk_mul_f32 v[160:161], v[160:161], s[40:41]
	v_pk_mul_f32 v[162:163], v[162:163], s[40:41]
	v_pk_mul_f32 v[164:165], v[164:165], s[40:41]
	v_pk_mul_f32 v[166:167], v[166:167], s[40:41]
	v_pk_mul_f32 v[168:169], v[168:169], s[40:41]
	v_pk_mul_f32 v[170:171], v[170:171], s[40:41]
	v_pk_mul_f32 v[172:173], v[172:173], s[40:41]
	v_pk_mul_f32 v[174:175], v[174:175], s[40:41]
	v_pk_mul_f32 v[176:177], v[176:177], s[40:41]
	v_pk_mul_f32 v[178:179], v[178:179], s[40:41]
	v_pk_mul_f32 v[180:181], v[180:181], s[40:41]
	v_pk_mul_f32 v[182:183], v[182:183], s[40:41]
	v_pk_mul_f32 v[186:187], v[186:187], s[40:41]
	v_pk_mul_f32 v[188:189], v[188:189], s[40:41]
	v_pk_mul_f32 v[190:191], v[190:191], s[40:41]
	v_pk_mul_f32 v[192:193], v[192:193], s[40:41]
	v_cvt_pk_fp8_f32 v128, v128, v132
	v_cvt_pk_fp8_f32 v129, v129, v133
	v_cvt_pk_fp8_f32 v130, v130, v134
	v_cvt_pk_fp8_f32 v131, v131, v135
	v_cvt_pk_fp8_f32 v128, v136, v140 op_sel:[0,0,1]
	v_cvt_pk_fp8_f32 v129, v137, v141 op_sel:[0,0,1]
	v_cvt_pk_fp8_f32 v130, v138, v142 op_sel:[0,0,1]
	v_cvt_pk_fp8_f32 v131, v139, v143 op_sel:[0,0,1]
	v_cvt_pk_fp8_f32 v144, v144, v148
	v_cvt_pk_fp8_f32 v145, v145, v149
	v_cvt_pk_fp8_f32 v146, v146, v150
	v_cvt_pk_fp8_f32 v147, v147, v151
	v_cvt_pk_fp8_f32 v144, v152, v156 op_sel:[0,0,1]
	v_cvt_pk_fp8_f32 v145, v153, v157 op_sel:[0,0,1]
	v_cvt_pk_fp8_f32 v146, v154, v158 op_sel:[0,0,1]
	v_cvt_pk_fp8_f32 v147, v155, v159 op_sel:[0,0,1]
	v_cvt_pk_fp8_f32 v160, v160, v164
	v_cvt_pk_fp8_f32 v161, v161, v165
	v_cvt_pk_fp8_f32 v162, v162, v166
	v_cvt_pk_fp8_f32 v163, v163, v167
	v_cvt_pk_fp8_f32 v160, v168, v172 op_sel:[0,0,1]
	v_cvt_pk_fp8_f32 v161, v169, v173 op_sel:[0,0,1]
	v_cvt_pk_fp8_f32 v162, v170, v174 op_sel:[0,0,1]
	v_cvt_pk_fp8_f32 v163, v171, v175 op_sel:[0,0,1]
	v_cvt_pk_fp8_f32 v176, v176, v180
	v_cvt_pk_fp8_f32 v177, v177, v181
	v_cvt_pk_fp8_f32 v178, v178, v182
	v_cvt_pk_fp8_f32 v179, v179, v183
	v_cvt_pk_fp8_f32 v176, v186, v190 op_sel:[0,0,1]
	v_cvt_pk_fp8_f32 v177, v187, v191 op_sel:[0,0,1]
	v_cvt_pk_fp8_f32 v178, v188, v192 op_sel:[0,0,1]
	v_cvt_pk_fp8_f32 v179, v189, v193 op_sel:[0,0,1]
	s_nop 0
	ds_write2_b32 v198, v128, v144 offset0:0 offset1:8
	ds_write2_b32 v198, v160, v176 offset0:16 offset1:24
	ds_write2_b32 v198, v129, v145 offset0:36 offset1:44
	ds_write2_b32 v198, v161, v177 offset0:52 offset1:60
	ds_write2_b32 v198, v130, v146 offset0:72 offset1:80
	ds_write2_b32 v198, v162, v178 offset0:88 offset1:96
	ds_write2_b32 v198, v131, v147 offset0:108 offset1:116
	ds_write2_b32 v198, v163, v179 offset0:124 offset1:132
	v_lshlrev_b32_e32 v136, s59, v200
	v_add_u32_e32 v136, v136, v201
	s_add_u32 s45, s59, 3
	s_lshl_b32 s4, 1, s45
	v_add_u32_e32 v152, s4, v136
	v_add_u32_e32 v168, s4, v152
	v_add_u32_e32 v186, s4, v168
	s_waitcnt lgkmcnt(0)
	ds_read_b128 v[132:135], v199 offset:0
	ds_read_b128 v[148:151], v199 offset:1152
	ds_read_b128 v[164:167], v199 offset:2304
	ds_read_b128 v[180:183], v199 offset:3456
	s_waitcnt lgkmcnt(3)
	global_store_dwordx4 v136, v[132:135], s[92:93]
	s_waitcnt lgkmcnt(2)
	global_store_dwordx4 v152, v[148:151], s[92:93]
	s_waitcnt lgkmcnt(1)
	global_store_dwordx4 v168, v[164:167], s[92:93]
	s_waitcnt lgkmcnt(0)
	global_store_dwordx4 v186, v[180:183], s[92:93]
	s_add_u32 s18, s18, 3
	s_cmp_lt_u32 s18, 24
	s_cbranch_scc1 .Lcp_loop
	s_waitcnt vmcnt(0)
	v_mov_b32_e32 v108, v184
	v_and_b32_e32 v146, 63, v108
	s_branch .Lscan_setup
	s_nop 0
	s_nop 0
	s_nop 0
	s_nop 0
	s_nop 0
	s_nop 0
	s_nop 0
	s_nop 0
	s_nop 0
	s_nop 0
	s_nop 0
	s_nop 0
	s_nop 0
	s_nop 0
	s_nop 0
	s_nop 0
	s_nop 0
	s_nop 0
	s_nop 0
	s_nop 0
	s_nop 0
	s_nop 0
	s_nop 0
	s_nop 0
	s_nop 0
	s_nop 0
	s_nop 0
	s_nop 0
	s_nop 0
	s_nop 0
	s_nop 0
	s_nop 0
	s_nop 0
	s_nop 0
	s_nop 0
	s_nop 0
	s_nop 0
	s_nop 0
	s_nop 0
	s_nop 0
	s_nop 0
	s_nop 0
	s_nop 0
	s_nop 0
	s_nop 0
	s_nop 0
	s_nop 0
	s_nop 0
	s_nop 0
	s_nop 0
	s_nop 0
	s_nop 0
	s_nop 0
	s_nop 0
	s_nop 0
	s_nop 0
	s_nop 0
	s_nop 0
	s_nop 0
	s_nop 0
	s_nop 0
	s_nop 0
	s_nop 0
	s_nop 0
	s_nop 0
	s_nop 0
	s_nop 0
	s_nop 0
	s_nop 0
	s_nop 0
	s_nop 0
	s_nop 0
	s_nop 0
	s_nop 0
	s_nop 0
	s_nop 0
	s_nop 0
	s_nop 0
	s_nop 0
	s_nop 0
	s_nop 0
	s_nop 0
	s_nop 0
	s_nop 0
	s_nop 0
	s_nop 0
	s_nop 0
	s_nop 0
	s_nop 0
	s_nop 0
	s_nop 0
	s_nop 0
	s_nop 0
	s_nop 0
	s_nop 0
	s_nop 0
	s_nop 0
	s_nop 0
	s_nop 0
	s_nop 0
	s_nop 0
	s_nop 0
	s_nop 0
	s_nop 0
	s_nop 0
	s_nop 0
	s_nop 0
	s_nop 0
	s_nop 0
	s_nop 0
	s_nop 0
	s_nop 0
	s_nop 0
	s_nop 0
	s_nop 0
	s_nop 0
	s_nop 0
	s_nop 0
	s_nop 0
	s_nop 0
	s_nop 0
	s_nop 0
	s_nop 0
	s_nop 0
	s_nop 0
	s_nop 0
	s_nop 0
	s_nop 0
	s_nop 0
	s_nop 0
	s_nop 0
	s_nop 0
	s_nop 0
	s_nop 0
	s_nop 0
	s_nop 0
	s_nop 0
	s_nop 0
	s_nop 0
	s_nop 0
	s_nop 0
	s_nop 0
	s_nop 0
	s_nop 0
	s_nop 0
	s_nop 0
	s_nop 0
	s_nop 0
	s_nop 0
	s_nop 0
	s_nop 0
	s_nop 0
	s_nop 0
	s_nop 0
	s_nop 0
	s_nop 0
	s_nop 0
	s_nop 0
	s_nop 0
	s_nop 0
	s_nop 0
	s_nop 0
	s_nop 0
	s_nop 0
	s_nop 0
	s_nop 0
	s_nop 0
	s_nop 0
	s_nop 0
	s_nop 0
	s_nop 0
	s_nop 0
	s_nop 0
	s_nop 0
	s_nop 0
	s_nop 0
	s_nop 0
	s_nop 0
	s_nop 0
	s_nop 0
	s_nop 0
	s_nop 0
	s_nop 0
	s_nop 0
	s_nop 0
	s_nop 0
	s_nop 0
	s_nop 0
	s_nop 0
	s_nop 0
	s_nop 0
	s_nop 0
	s_nop 0
	s_nop 0
	s_nop 0
	s_nop 0
	s_nop 0
	s_nop 0
	s_nop 0
	s_nop 0
	s_nop 0
	s_nop 0
	s_nop 0
	s_nop 0
	s_nop 0
	s_nop 0
	s_nop 0
	s_nop 0
	s_nop 0
	s_nop 0
	s_nop 0
	s_nop 0
	s_nop 0
	s_nop 0
	s_nop 0
	s_nop 0
	s_nop 0
	s_nop 0
	s_nop 0
	s_nop 0
	s_nop 0
	s_nop 0
	s_nop 0
	s_nop 0
	s_nop 0
	s_nop 0
	s_nop 0
	s_nop 0
	s_nop 0
	s_nop 0
	s_nop 0
	s_nop 0
	s_nop 0
	s_nop 0
	s_nop 0
	s_nop 0
	s_nop 0
	s_nop 0
	s_nop 0
	s_nop 0
	s_nop 0
	s_nop 0
	s_nop 0
	s_nop 0
	s_nop 0
	s_nop 0
	s_nop 0
	s_nop 0
	s_nop 0
	s_nop 0
	s_nop 0
	s_nop 0
	s_nop 0
	s_nop 0
	s_nop 0
	s_nop 0
	s_nop 0
	s_nop 0
	s_nop 0
	s_nop 0
	s_nop 0
	s_nop 0
	s_nop 0
	s_nop 0
	s_nop 0
	s_nop 0
	s_nop 0
	s_nop 0
	s_nop 0
	s_nop 0
	s_nop 0
	s_nop 0
	s_nop 0
	s_nop 0
	s_nop 0
	s_nop 0
	s_nop 0
	s_nop 0
	s_nop 0
	s_nop 0
	s_nop 0
	s_nop 0
	s_nop 0
	s_nop 0
	s_nop 0
	s_nop 0
	s_nop 0
	s_nop 0
	s_nop 0
	s_nop 0
	s_nop 0
	s_nop 0
	s_nop 0
	s_nop 0
	s_nop 0
	s_nop 0
	s_nop 0
	s_nop 0
	s_nop 0
	s_nop 0
	s_nop 0
	s_nop 0
	s_nop 0
	s_nop 0
	s_nop 0
	s_nop 0
	s_nop 0
	s_nop 0
	s_nop 0
	s_nop 0
	s_nop 0
	s_nop 0
	s_nop 0
	s_nop 0
	s_nop 0
	s_nop 0
	s_nop 0
	s_nop 0
	s_nop 0
	s_nop 0
	s_nop 0
	s_nop 0
	s_nop 0
	s_nop 0
	s_nop 0
	s_nop 0
	s_nop 0
	s_nop 0
	s_nop 0
	s_nop 0
	s_nop 0
	s_nop 0
	s_nop 0
	s_nop 0
	s_nop 0
	s_nop 0
	s_nop 0
	s_nop 0
	s_nop 0
	s_nop 0
	s_nop 0
	s_nop 0
	s_nop 0
	s_nop 0
	s_nop 0
	s_nop 0
	s_nop 0
	s_nop 0
	s_nop 0
	s_nop 0
	s_nop 0
	s_nop 0
	s_nop 0
	s_nop 0
	s_nop 0
	s_nop 0
	s_nop 0
	s_nop 0
	s_nop 0
	s_nop 0
	s_nop 0
	s_nop 0
	s_nop 0
	s_nop 0
	s_nop 0
	s_nop 0
	s_nop 0
	s_nop 0
	s_nop 0
	s_nop 0
	s_nop 0
	s_nop 0
	s_nop 0
	s_nop 0
	s_nop 0
	s_nop 0
	s_nop 0
	s_nop 0
	s_nop 0
	s_nop 0
	s_nop 0
	s_nop 0
	s_nop 0
	s_nop 0
	s_nop 0
	s_nop 0
	s_nop 0
	s_nop 0
	s_nop 0
	s_nop 0
	s_nop 0
	s_nop 0
	s_nop 0
	s_nop 0
	s_nop 0
	s_nop 0
	s_nop 0
	s_nop 0
	s_nop 0
	s_nop 0
	s_nop 0
	s_nop 0
	s_nop 0
	s_nop 0
	s_nop 0
	s_nop 0
	s_nop 0
	s_nop 0
	s_nop 0
	s_nop 0
	s_nop 0
	s_nop 0
	s_nop 0
	s_nop 0
	s_nop 0
	s_nop 0
	s_nop 0
	s_nop 0
	s_nop 0
	s_nop 0
	s_nop 0
	s_nop 0
	s_nop 0
	s_nop 0
	s_nop 0
	s_nop 0
	s_nop 0
	s_nop 0
	s_nop 0
	s_nop 0
	s_nop 0
	s_nop 0
	s_nop 0
	s_nop 0
	s_nop 0
	s_nop 0
	s_nop 0
	s_nop 0
	s_nop 0
	s_nop 0
	s_nop 0
	s_nop 0
	s_nop 0
	s_nop 0
	s_nop 0
	s_nop 0
	s_nop 0
	s_nop 0
	s_nop 0
	s_nop 0
	s_nop 0
	s_nop 0
	s_nop 0
	s_nop 0
	s_nop 0
	s_nop 0
	s_nop 0
	s_nop 0
	s_nop 0
	s_nop 0
	s_nop 0
	s_nop 0
	s_nop 0
	s_nop 0
	s_nop 0
	s_nop 0
	s_nop 0
	s_nop 0
	s_nop 0
	s_nop 0
	s_nop 0
	s_nop 0
	s_nop 0
	s_nop 0
	s_nop 0
	s_nop 0
	s_nop 0
	s_nop 0
	s_nop 0
	s_nop 0
	s_nop 0
	s_nop 0
	s_nop 0
	s_nop 0
	s_nop 0
	s_nop 0
	s_nop 0
	s_nop 0
	s_nop 0
	s_nop 0
	s_nop 0
	s_nop 0
	s_nop 0
	s_nop 0
	s_nop 0
	s_nop 0
	s_nop 0
	s_nop 0
	s_nop 0
	s_nop 0
	s_nop 0
	s_nop 0
	s_nop 0
	s_nop 0
	s_nop 0
	s_nop 0
	s_nop 0
	s_nop 0
	s_nop 0
	s_nop 0
	s_nop 0
	s_nop 0
	s_nop 0
	s_nop 0
	s_nop 0
	s_nop 0
	s_nop 0
	s_nop 0
	s_nop 0
	s_nop 0
	s_nop 0
	s_nop 0
	s_nop 0
	s_nop 0
	s_nop 0
	s_nop 0
	s_nop 0
	s_nop 0
	s_nop 0
	s_nop 0
	s_nop 0
	s_nop 0
	s_nop 0
	s_nop 0
	s_nop 0
	s_nop 0
	s_nop 0
	s_nop 0
	s_nop 0
	s_nop 0
	s_nop 0
	s_nop 0
	s_nop 0
	s_nop 0
	s_nop 0
	s_nop 0
	s_nop 0
	s_nop 0
	s_nop 0
	s_nop 0
	s_nop 0
	s_nop 0
	s_nop 0
	s_nop 0
	s_nop 0
	s_nop 0
	s_nop 0
	s_nop 0
	s_nop 0
	s_nop 0
	s_nop 0
	s_nop 0
	s_nop 0
	s_nop 0
	s_nop 0
	s_nop 0
	s_nop 0
	s_nop 0
	s_nop 0
	s_nop 0
	s_nop 0
	s_nop 0
	s_nop 0
	s_nop 0
	s_nop 0
	s_nop 0
	s_nop 0
	s_nop 0
	s_nop 0
	s_nop 0
	s_nop 0
	s_nop 0
	s_nop 0
	s_nop 0
	s_nop 0
	s_nop 0
	s_nop 0
	s_nop 0
	s_nop 0
	s_nop 0
	s_nop 0
	s_nop 0
	s_nop 0
	s_nop 0
	s_nop 0
	s_nop 0
	s_nop 0
	s_nop 0
	s_nop 0
	s_nop 0
	s_nop 0
	s_nop 0
	s_nop 0
	s_nop 0
	s_nop 0
	s_nop 0
	s_nop 0
	s_nop 0
	s_nop 0
	s_nop 0
	s_nop 0
	s_nop 0
	s_nop 0
	s_nop 0
	s_nop 0
	s_nop 0
	s_nop 0
	s_nop 0
	s_nop 0
	s_nop 0
	s_nop 0
	s_nop 0
	s_nop 0
	s_nop 0
	s_nop 0
	s_nop 0
	s_nop 0
	s_nop 0
	s_nop 0
	s_nop 0
	s_nop 0
	s_nop 0
	s_nop 0
	s_nop 0
	s_nop 0
	s_nop 0
	s_nop 0
	s_nop 0
	s_nop 0
	s_nop 0
	s_nop 0
	s_nop 0
	s_nop 0
	s_nop 0
	s_nop 0
	s_nop 0
	s_nop 0
	s_nop 0
	s_nop 0
	s_nop 0
	s_nop 0
	s_nop 0
	s_nop 0
	s_nop 0
	s_nop 0
	s_nop 0
	s_nop 0
	s_nop 0
	s_nop 0
	s_nop 0
	s_nop 0
	s_nop 0
	s_nop 0
	s_nop 0
	s_nop 0
	s_nop 0
	s_nop 0
	s_nop 0
	s_nop 0
	s_nop 0
	s_nop 0
	s_nop 0
	s_nop 0
	s_nop 0
	s_nop 0
	s_nop 0
	s_nop 0
	s_nop 0
	s_nop 0
	s_nop 0
	s_nop 0
	s_nop 0
	s_nop 0
	s_nop 0
	s_nop 0
	s_nop 0
	s_nop 0
	s_nop 0
	s_nop 0
	s_nop 0
	s_nop 0
	s_nop 0
	s_nop 0
	s_nop 0
	s_nop 0
	s_nop 0
	s_nop 0
	s_nop 0
	s_nop 0
	s_nop 0
	s_nop 0
	s_nop 0
	s_nop 0
	s_nop 0
	s_nop 0
	s_nop 0
	s_nop 0
	s_nop 0
	s_nop 0
	s_nop 0
	s_nop 0
	s_nop 0
	s_nop 0
	s_nop 0
	s_nop 0
	s_nop 0
	s_nop 0
	s_nop 0
	s_nop 0
	s_nop 0
	s_nop 0
	s_nop 0
	s_nop 0
	s_nop 0
	s_nop 0
	s_nop 0
	s_nop 0
	s_nop 0
	s_nop 0
	s_nop 0
	s_nop 0
	s_nop 0
	s_nop 0
	s_nop 0
	s_nop 0
	s_nop 0
	s_nop 0
	s_nop 0
	s_nop 0
	s_nop 0
	s_nop 0
	s_nop 0
	s_nop 0
	s_nop 0
	s_nop 0
	s_nop 0
	s_nop 0
	s_nop 0
	s_nop 0
	s_nop 0
	s_nop 0
	s_nop 0
	s_nop 0
	s_nop 0
	s_nop 0
	s_nop 0
	s_nop 0
	s_nop 0
	s_nop 0
	s_nop 0
	s_nop 0
	s_nop 0
	s_nop 0
	s_nop 0
	s_nop 0
	s_nop 0
	s_nop 0
	s_nop 0
	s_nop 0
	s_nop 0
	s_nop 0
	s_nop 0
	s_nop 0
	s_nop 0
	s_nop 0
	s_nop 0
	s_nop 0
	s_nop 0
	s_nop 0
	s_nop 0
	s_nop 0
	s_nop 0
	s_nop 0
	s_nop 0
	s_nop 0
	s_nop 0
	s_nop 0
	s_nop 0
	s_nop 0
	s_nop 0
	s_nop 0
	s_nop 0
	s_nop 0
	s_nop 0
	s_nop 0
	s_nop 0
	s_nop 0
	s_nop 0
	s_nop 0
	s_nop 0
	s_nop 0
	s_nop 0
	s_nop 0
	s_nop 0
	s_nop 0
	s_nop 0
	s_nop 0
	s_nop 0
	s_nop 0
	s_nop 0
	s_nop 0
	s_nop 0
	s_nop 0
	s_nop 0
	s_nop 0
	s_nop 0
	s_nop 0
	s_nop 0
	s_nop 0
	s_nop 0
	s_nop 0
	s_nop 0
	s_nop 0
	s_nop 0
	s_nop 0
	s_nop 0
	s_nop 0
	s_nop 0
	s_nop 0
	s_nop 0
	s_nop 0
	s_nop 0
	s_nop 0
	s_nop 0
	s_nop 0
	s_nop 0
	s_nop 0
	s_nop 0
	s_nop 0
	s_nop 0
	s_nop 0
	s_nop 0
	s_nop 0
	s_nop 0
	s_nop 0
	s_nop 0
	s_nop 0
	s_nop 0
	s_nop 0
	s_nop 0
	s_nop 0
	s_nop 0
	s_nop 0
	s_nop 0
	s_nop 0
	s_nop 0
	s_nop 0
	s_nop 0
	s_nop 0
	s_nop 0
	s_nop 0
	s_nop 0
	s_nop 0
	s_nop 0
	s_nop 0
	s_nop 0
	s_nop 0
	s_nop 0
	s_nop 0
	s_nop 0
	s_nop 0
	s_nop 0
	s_nop 0
	s_nop 0
	s_nop 0
	s_nop 0
	s_nop 0
	s_nop 0
	s_nop 0
	s_nop 0
	s_nop 0
	s_nop 0
	s_nop 0
	s_nop 0
	s_nop 0
	s_nop 0
	s_nop 0
	s_nop 0
	s_nop 0
	s_nop 0
	s_nop 0
	s_nop 0
	s_nop 0
	s_nop 0
	s_nop 0
	s_nop 0
	s_nop 0
	s_nop 0
	s_nop 0
	s_nop 0
	s_nop 0
	s_nop 0
	s_nop 0
	s_nop 0
	s_nop 0
	s_nop 0
	s_nop 0
	s_nop 0
	s_nop 0
	s_nop 0
	s_nop 0
	s_nop 0
	s_nop 0
	s_nop 0
	s_nop 0
	s_nop 0
	s_nop 0
	s_nop 0
	s_nop 0
	s_nop 0
	s_nop 0
	s_nop 0
	s_nop 0
	s_nop 0
	s_nop 0
	s_nop 0
	s_nop 0
	s_nop 0
	s_nop 0
	s_nop 0
	s_nop 0
	s_nop 0
	s_nop 0
	s_nop 0
	s_nop 0
	s_nop 0
	s_nop 0
	s_nop 0
	s_nop 0
	s_nop 0
	s_nop 0
	s_nop 0
	s_nop 0
	s_nop 0
	s_nop 0
	s_nop 0
	s_nop 0
	s_nop 0
	s_nop 0
	s_nop 0
	s_nop 0
	s_nop 0
	s_nop 0
	s_nop 0
	s_nop 0
	s_nop 0
	s_nop 0
	s_nop 0
	s_nop 0
	s_nop 0
	s_nop 0
	s_nop 0
	s_nop 0
	s_nop 0
	s_nop 0
	s_nop 0
	s_nop 0
	s_nop 0
	s_nop 0
	s_nop 0
	s_nop 0
	s_nop 0
	s_nop 0
	s_nop 0
	s_nop 0
	s_nop 0
	s_nop 0
	s_nop 0
	s_nop 0
	s_nop 0
	s_nop 0
	s_nop 0
	s_nop 0
	s_nop 0
	s_nop 0
	s_nop 0
	s_nop 0
	s_nop 0
	s_nop 0
	s_nop 0
	s_nop 0
	s_nop 0
	s_nop 0
	s_nop 0
	s_nop 0
	s_nop 0
	s_nop 0
	s_nop 0
	s_nop 0
	s_nop 0
	s_nop 0
	s_nop 0
	s_nop 0
	s_nop 0
	s_nop 0
	s_nop 0
	s_nop 0
	s_nop 0
	s_nop 0
	s_nop 0
	s_nop 0
	s_nop 0
	s_nop 0
	s_nop 0
	s_nop 0
	s_nop 0
	s_nop 0
	s_nop 0
	s_nop 0
	s_nop 0
	s_nop 0
	s_nop 0
	s_nop 0
	s_nop 0
	s_nop 0
	s_nop 0
	s_nop 0
	s_nop 0
	s_nop 0
	s_nop 0
	s_nop 0
	s_nop 0
	s_nop 0
	s_nop 0
	s_nop 0
	s_nop 0
	s_nop 0
	s_nop 0
	s_nop 0
	s_nop 0
	s_nop 0
	s_nop 0
	s_nop 0
	s_nop 0
	s_nop 0
	s_nop 0
	s_nop 0
	s_nop 0
	s_nop 0
	s_nop 0
	s_nop 0
	s_nop 0
	s_nop 0
	s_nop 0
	s_nop 0
	s_nop 0
	s_nop 0
	s_nop 0
	s_nop 0
	s_nop 0
	s_nop 0
	s_nop 0
	s_nop 0
	s_nop 0
	s_nop 0
	s_nop 0
	s_nop 0
	s_nop 0
	s_nop 0
	s_nop 0
	s_nop 0
	s_nop 0
	s_nop 0
	s_nop 0
	s_nop 0
	s_nop 0
	s_nop 0
	s_nop 0
	s_nop 0
	s_nop 0
	s_nop 0
	s_nop 0
	s_nop 0
	s_nop 0
	s_nop 0
	s_nop 0
	s_nop 0
	s_nop 0
	s_nop 0
	s_nop 0
	s_nop 0
	s_nop 0
	s_nop 0
	s_nop 0
	s_nop 0
	s_nop 0
	s_nop 0
	s_nop 0
	s_nop 0
	s_nop 0
	s_nop 0
	s_nop 0
	s_nop 0
	s_nop 0
	s_nop 0
	s_nop 0
	s_nop 0
	s_nop 0
	s_nop 0
	s_nop 0
	s_nop 0
	s_nop 0
	s_nop 0
	s_nop 0
	s_nop 0
	s_nop 0
	s_nop 0
	s_nop 0
	s_nop 0
	s_nop 0
	s_nop 0
	s_nop 0
	s_nop 0
	s_nop 0
	s_nop 0
	s_nop 0
	s_nop 0
	s_nop 0
	s_nop 0
	s_nop 0
	s_nop 0
	s_nop 0
	s_nop 0
	s_nop 0
	s_nop 0
	s_nop 0
	s_nop 0
	s_nop 0
	s_nop 0
	s_nop 0
	s_nop 0
	s_nop 0
	s_nop 0
	s_nop 0
	s_nop 0
	s_nop 0
	s_nop 0
	s_nop 0
	s_nop 0
	s_nop 0
	s_nop 0
	s_nop 0
	s_nop 0
	s_nop 0
	s_nop 0
	s_nop 0
	s_nop 0
	s_nop 0
	s_nop 0
	s_nop 0
	s_nop 0
	s_nop 0
	s_nop 0
	s_nop 0
	s_nop 0
	s_nop 0
	s_nop 0
	s_nop 0
	s_nop 0
	s_nop 0
	s_nop 0
	s_nop 0
	s_nop 0
	s_nop 0
	s_nop 0
	s_nop 0
	s_nop 0
	s_nop 0
	s_nop 0
	s_nop 0
	s_nop 0
	s_nop 0
	s_nop 0
	s_nop 0
	s_nop 0
	s_nop 0
	s_nop 0
	s_nop 0
	s_nop 0
	s_nop 0
	s_nop 0
	s_nop 0
	s_nop 0
	s_nop 0
	s_nop 0
	s_nop 0
	s_nop 0
	s_nop 0
	s_nop 0
	s_nop 0
	s_nop 0
	s_nop 0
	s_nop 0
	s_nop 0
	s_nop 0
	s_nop 0
	s_nop 0
	s_nop 0
	s_nop 0
	s_nop 0
	s_nop 0
	s_nop 0
	s_nop 0
	s_nop 0
	s_nop 0
	s_nop 0
	s_nop 0
	s_nop 0
	s_nop 0
	s_nop 0
	s_nop 0
	s_nop 0
	s_nop 0
	s_nop 0
	s_nop 0
	s_nop 0
	s_nop 0
	s_nop 0
	s_nop 0
	s_nop 0
	s_nop 0
	s_nop 0
	s_nop 0
	s_nop 0
	s_nop 0
	s_nop 0
	s_nop 0
	s_nop 0
	s_nop 0
	s_nop 0
	s_nop 0
	s_nop 0
	s_nop 0
	s_nop 0
	s_nop 0
	s_nop 0
	s_nop 0
	s_nop 0
	s_nop 0
	s_nop 0
	s_nop 0
	s_nop 0
	s_nop 0
	s_nop 0
	s_nop 0
	s_nop 0
	s_nop 0
	s_nop 0
	s_nop 0
	s_nop 0
	s_nop 0
	s_nop 0
	s_nop 0
	s_nop 0
	s_nop 0
	s_nop 0
	s_nop 0
	s_nop 0
	s_nop 0
	s_nop 0
	s_nop 0
	s_nop 0
	s_nop 0
	s_nop 0
	s_nop 0
	s_nop 0
	s_nop 0
	s_nop 0
	s_nop 0
	s_nop 0
	s_nop 0
	s_nop 0
	s_nop 0
	s_nop 0
	s_nop 0
	s_nop 0
	s_nop 0
	s_nop 0
	s_nop 0
	s_nop 0
	s_nop 0
	s_nop 0
	s_nop 0
	s_nop 0
	s_nop 0
	s_nop 0
	s_nop 0
	s_nop 0
	s_nop 0
	s_nop 0
	s_nop 0
	s_nop 0
	s_nop 0
	s_nop 0
	s_nop 0
	s_nop 0
	s_nop 0
	s_nop 0
	s_nop 0
	s_nop 0
	s_nop 0
	s_nop 0
	s_nop 0
	s_nop 0
	s_nop 0
	s_nop 0
	s_nop 0
	s_nop 0
	s_nop 0
	s_nop 0
	s_nop 0
	s_nop 0
	s_nop 0
	s_nop 0
	s_nop 0
	s_nop 0
	s_nop 0
	s_nop 0
	s_nop 0
	s_nop 0
	s_nop 0
	s_nop 0
	s_nop 0
	s_nop 0
	s_nop 0
	s_nop 0
	s_nop 0
	s_nop 0
	s_nop 0
	s_nop 0
	s_nop 0
	s_nop 0
	s_nop 0
	s_nop 0
	s_nop 0
	s_nop 0
	s_nop 0
	s_nop 0
	s_nop 0
	s_nop 0
	s_nop 0
	s_nop 0
	s_nop 0
	s_nop 0
	s_nop 0
	s_nop 0
